# GEMM K-loops: pointer selects and address moves that sat between a load segment's last wait and its closing barrier moved in front of the wait
# speedup vs baseline: 1.0004x; 1.0004x over previous
; #define PG8_STAGE(bufoff, gbase, voff) do { _Pragma("unroll") for (int _i = 0; _i < 2; ++_i) \
;         __builtin_amdgcn_global_load_lds((const unsigned*)((const char*)(gbase) + (voff)[_i]), (PG8_LAS unsigned*)(lds + (bufoff) + ldsw + _i * 8192), 16, 0, 0); } while (0)
; #define PG8_LDA(dst, b, h) do { _Pragma("unroll") for (int m = 0; m < 4; ++m) _Pragma("unroll") for (int k = 0; k < 2; ++k) dst[m][k] = *(const PG8_LAS bf16x8*)(lds + PG8_SA(b, h) + aoff + m * 2048 + k * 1024); } while (0)
; #define PG8_LDB(dst, b, h) do { _Pragma("unroll") for (int n = 0; n < 2; ++n) _Pragma("unroll") for (int k = 0; k < 2; ++k) dst[n][k] = *(const PG8_LAS bf16x8*)(lds + PG8_SB(b, h) + boff + n * 2048 + k * 1024); } while (0)
; #define PG8_WAIT_VR(relax) do { if (relax) asm volatile("s_waitcnt vmcnt(%0)" :: "n"(8 + Epi::NST) : "memory"); else asm volatile("s_waitcnt vmcnt(8)" ::: "memory"); } while (0)
; #define PG8_WAIT_L(n) asm volatile("s_waitcnt lgkmcnt(" #n ")" ::: "memory")
; #define PG8_BAR __builtin_amdgcn_s_barrier()
; #define PG8_SCHED __builtin_amdgcn_sched_barrier(0)
; template <class Epi, class Sched, bool ALIGN_EPI = false, bool SP2 = false, bool F8 = false, bool GATHER = false>
; __device__ __forceinline__ void gemm_phase(PG8_LAS unsigned char* lds, const Gemm g, const Sched& S, const Epi& E, const int tid_in) {
;     ...
;             const char* a2 = last ? nA : cA + (size_t)(t + 2) * kstep; const char* b2 = last ? nB : cB + (size_t)(t + 2) * kstep;
;             const char* a3 = a2 + kstep; const char* b3 = b2 + kstep;
;             if (last && has_next) S.a_ready(nxt);
;             const bool relax = SP2 && ALIGN_EPI && t == 0 && ui > 0;
;             if constexpr (SP2) {
;             PG8_LDB(B0, 0, 0); PG8_LDB(B1, 0, 1); PG8_SCHED; PG8_LDA(At, 0, 0); if (!relax) PG8_STAGE(PG8_SA(1, 1), a1 + hstepA, vA1c);
;             PG8_WAIT_VR(relax); PG8_WAIT_L(0); PG8_BAR; PG8_MMA(0, 0, At, B0); PG8_MMA(0, 1, At, B1); PG8_BAR; PG8_SCHED;
;             PG8_LDA(At, 0, 1); PG8_STAGE(PG8_SB(0, 0), b2, voffB); PG8_STAGE(PG8_SB(0, 1), b2 + hstep, voffB); PG8_STAGE(PG8_SA(0, 0), a2, vA0s);
.LBB0_161:
	s_xor_b64 s[52:53], s[50:51], -1
	s_add_u32 s50, s40, s48
	s_addc_u32 s51, s41, s49
	s_add_u32 s50, s50, 0x100
	s_addc_u32 s51, s51, 0
	s_add_u32 s56, s77, s48
	s_addc_u32 s57, s78, s49
	s_cmpk_eq_i32 s48, 0x700
	s_cselect_b32 s55, s37, s51
	s_cselect_b32 s54, s75, s50
	s_cselect_b32 s51, s23, s57
	s_cselect_b32 s50, s76, s56
	s_waitcnt lgkmcnt(0)
	s_barrier
	s_setprio 1
	s_waitcnt lgkmcnt(0)
	v_mfma_f32_16x16x32_bf16 v[128:131], v[148:151], v[188:191], v[128:131]
	v_mfma_f32_16x16x32_bf16 v[124:127], v[156:159], v[188:191], v[124:127]
	v_mfma_f32_16x16x32_bf16 v[120:123], v[148:151], v[180:183], v[120:123]
	v_mfma_f32_16x16x32_bf16 v[112:115], v[156:159], v[180:183], v[112:115]
	v_mfma_f32_16x16x32_bf16 v[104:107], v[148:151], v[172:175], v[104:107]
	v_mfma_f32_16x16x32_bf16 v[96:99], v[156:159], v[172:175], v[96:99]
	v_mfma_f32_16x16x32_bf16 v[88:91], v[148:151], v[164:167], v[88:91]
	v_mfma_f32_16x16x32_bf16 v[80:83], v[156:159], v[164:167], v[80:83]
	v_mfma_f32_16x16x32_bf16 v[128:131], v[152:155], v[192:195], v[128:131]
	v_mfma_f32_16x16x32_bf16 v[124:127], v[160:163], v[192:195], v[124:127]
	v_mfma_f32_16x16x32_bf16 v[120:123], v[152:155], v[184:187], v[120:123]
	v_mfma_f32_16x16x32_bf16 v[112:115], v[160:163], v[184:187], v[112:115]
	v_mfma_f32_16x16x32_bf16 v[104:107], v[152:155], v[176:179], v[104:107]
	v_mfma_f32_16x16x32_bf16 v[96:99], v[160:163], v[176:179], v[96:99]
	v_mfma_f32_16x16x32_bf16 v[88:91], v[152:155], v[168:171], v[88:91]
	v_mfma_f32_16x16x32_bf16 v[80:83], v[160:163], v[168:171], v[80:83]
	s_setprio 0
	s_setprio 1
	v_mfma_f32_16x16x32_bf16 v[116:119], v[132:135], v[188:191], v[116:119]
	v_mfma_f32_16x16x32_bf16 v[108:111], v[140:143], v[188:191], v[108:111]
	v_mfma_f32_16x16x32_bf16 v[100:103], v[132:135], v[180:183], v[100:103]
	v_mfma_f32_16x16x32_bf16 v[92:95], v[140:143], v[180:183], v[92:95]
	v_mfma_f32_16x16x32_bf16 v[84:87], v[132:135], v[172:175], v[84:87]
	v_mfma_f32_16x16x32_bf16 v[76:79], v[140:143], v[172:175], v[76:79]
	v_mfma_f32_16x16x32_bf16 v[72:75], v[132:135], v[164:167], v[72:75]
	v_mfma_f32_16x16x32_bf16 v[68:71], v[140:143], v[164:167], v[68:71]
	v_mfma_f32_16x16x32_bf16 v[116:119], v[136:139], v[192:195], v[116:119]
	v_mfma_f32_16x16x32_bf16 v[108:111], v[144:147], v[192:195], v[108:111]
	v_mfma_f32_16x16x32_bf16 v[100:103], v[136:139], v[184:187], v[100:103]
	v_mfma_f32_16x16x32_bf16 v[92:95], v[144:147], v[184:187], v[92:95]
	v_mfma_f32_16x16x32_bf16 v[84:87], v[136:139], v[176:179], v[84:87]
	v_mfma_f32_16x16x32_bf16 v[76:79], v[144:147], v[176:179], v[76:79]
	v_mfma_f32_16x16x32_bf16 v[72:75], v[136:139], v[168:171], v[72:75]
	v_mfma_f32_16x16x32_bf16 v[68:71], v[144:147], v[168:171], v[68:71]
	s_setprio 0
	s_barrier
	s_mov_b32 m0, s34
	v_lshl_add_u64 v[218:219], s[50:51], 0, v[206:207]
	s_add_u32 s56, s50, 0x40000
	ds_read_b128 v[188:191], v232 offset:16384
	ds_read_b128 v[192:195], v232 offset:17408
	ds_read_b128 v[180:183], v232 offset:18432
	ds_read_b128 v[184:187], v232 offset:19456
	ds_read_b128 v[172:175], v232 offset:20480
	ds_read_b128 v[176:179], v232 offset:21504
	ds_read_b128 v[164:167], v232 offset:22528
	ds_read_b128 v[168:171], v232 offset:23552
	global_load_lds_dwordx4 v[218:219], off
	v_lshl_add_u64 v[220:221], s[50:51], 0, v[202:203]
	s_mov_b32 m0, s35
	s_addc_u32 s57, s51, 0
	global_load_lds_dwordx4 v[220:221], off
	v_lshl_add_u64 v[222:223], s[56:57], 0, v[206:207]
	s_mov_b32 m0, s58
	v_lshl_add_u64 v[224:225], s[54:55], 0, v[204:205]
	global_load_lds_dwordx4 v[222:223], off
	v_lshl_add_u64 v[222:223], s[56:57], 0, v[202:203]
	s_mov_b32 m0, s59
	s_mov_b64 s[56:57], -1
	global_load_lds_dwordx4 v[222:223], off
	v_lshl_add_u64 v[222:223], s[54:55], 0, v[208:209]
	s_mov_b32 m0, s25
	s_and_b64 vcc, exec, s[52:53]
	global_load_lds_dwordx4 v[222:223], off
	s_mov_b32 m0, s60
	s_nop 0
	global_load_lds_dwordx4 v[224:225], off
	s_cbranch_vccz .LBB0_163
	s_waitcnt vmcnt(8)
	s_mov_b64 s[56:57], 0

; #define PG8_STAGE(bufoff, gbase, voff) do { _Pragma("unroll") for (int _i = 0; _i < 2; ++_i) \
;         __builtin_amdgcn_global_load_lds((const unsigned*)((const char*)(gbase) + (voff)[_i]), (PG8_LAS unsigned*)(lds + (bufoff) + ldsw + _i * 8192), 16, 0, 0); } while (0)
; #define PG8_LDA(dst, b, h) do { _Pragma("unroll") for (int m = 0; m < 4; ++m) _Pragma("unroll") for (int k = 0; k < 2; ++k) dst[m][k] = *(const PG8_LAS bf16x8*)(lds + PG8_SA(b, h) + aoff + m * 2048 + k * 1024); } while (0)
; #define PG8_LDB(dst, b, h) do { _Pragma("unroll") for (int n = 0; n < 2; ++n) _Pragma("unroll") for (int k = 0; k < 2; ++k) dst[n][k] = *(const PG8_LAS bf16x8*)(lds + PG8_SB(b, h) + boff + n * 2048 + k * 1024); } while (0)
; #define PG8_WAIT_VR(relax) do { if (relax) asm volatile("s_waitcnt vmcnt(%0)" :: "n"(8 + Epi::NST) : "memory"); else asm volatile("s_waitcnt vmcnt(8)" ::: "memory"); } while (0)
; #define PG8_WAIT_L(n) asm volatile("s_waitcnt lgkmcnt(" #n ")" ::: "memory")
; #define PG8_BAR __builtin_amdgcn_s_barrier()
; #define PG8_SCHED __builtin_amdgcn_sched_barrier(0)
; template <class Epi, class Sched, bool ALIGN_EPI = false, bool SP2 = false, bool F8 = false, bool GATHER = false>
; __device__ __forceinline__ void gemm_phase(PG8_LAS unsigned char* lds, const Gemm g, const Sched& S, const Epi& E, const int tid_in) {
;     ...
;             const char* a2 = last ? nA : cA + (size_t)(t + 2) * kstep; const char* b2 = last ? nB : cB + (size_t)(t + 2) * kstep;
;             const char* a3 = a2 + kstep; const char* b3 = b2 + kstep;
;             if (last && has_next) S.a_ready(nxt);
;             const bool relax = SP2 && ALIGN_EPI && t == 0 && ui > 0;
;             if constexpr (SP2) {
;             PG8_LDB(B0, 0, 0); PG8_LDB(B1, 0, 1); PG8_SCHED; PG8_LDA(At, 0, 0); if (!relax) PG8_STAGE(PG8_SA(1, 1), a1 + hstepA, vA1c);
;             PG8_WAIT_VR(relax); PG8_WAIT_L(0); PG8_BAR; PG8_MMA(0, 0, At, B0); PG8_MMA(0, 1, At, B1); PG8_BAR; PG8_SCHED;
;             PG8_LDA(At, 0, 1); PG8_STAGE(PG8_SB(0, 0), b2, voffB); PG8_STAGE(PG8_SB(0, 1), b2 + hstep, voffB); PG8_STAGE(PG8_SA(0, 0), a2, vA0s);
.Lpk_inproj_161:
	s_xor_b64 s[52:53], s[50:51], -1
	s_add_u32 s50, s40, s48
	s_addc_u32 s51, s41, s49
	s_add_u32 s50, s50, 0x100
	s_addc_u32 s51, s51, 0
	s_add_u32 s56, s77, s48
	s_addc_u32 s57, s78, s49
	s_cmpk_eq_i32 s48, 0x700
	s_cselect_b32 s55, s37, s51
	s_cselect_b32 s54, s75, s50
	s_cselect_b32 s51, s23, s57
	s_cselect_b32 s50, s76, s56
	s_waitcnt lgkmcnt(0)
	s_barrier
	s_setprio 1
	s_waitcnt lgkmcnt(0)
	v_mfma_f32_16x16x32_bf16 v[128:131], v[148:151], v[188:191], 0
	v_mfma_f32_16x16x32_bf16 v[124:127], v[156:159], v[188:191], 0
	v_mfma_f32_16x16x32_bf16 v[120:123], v[148:151], v[180:183], 0
	v_mfma_f32_16x16x32_bf16 v[112:115], v[156:159], v[180:183], 0
	v_mfma_f32_16x16x32_bf16 v[104:107], v[148:151], v[172:175], 0
	v_mfma_f32_16x16x32_bf16 v[96:99], v[156:159], v[172:175], 0
	v_mfma_f32_16x16x32_bf16 v[88:91], v[148:151], v[164:167], 0
	v_mfma_f32_16x16x32_bf16 v[80:83], v[156:159], v[164:167], 0
	v_mfma_f32_16x16x32_bf16 v[128:131], v[152:155], v[192:195], v[128:131]
	v_mfma_f32_16x16x32_bf16 v[124:127], v[160:163], v[192:195], v[124:127]
	v_mfma_f32_16x16x32_bf16 v[120:123], v[152:155], v[184:187], v[120:123]
	v_mfma_f32_16x16x32_bf16 v[112:115], v[160:163], v[184:187], v[112:115]
	v_mfma_f32_16x16x32_bf16 v[104:107], v[152:155], v[176:179], v[104:107]
	v_mfma_f32_16x16x32_bf16 v[96:99], v[160:163], v[176:179], v[96:99]
	v_mfma_f32_16x16x32_bf16 v[88:91], v[152:155], v[168:171], v[88:91]
	v_mfma_f32_16x16x32_bf16 v[80:83], v[160:163], v[168:171], v[80:83]
	s_setprio 0
	s_setprio 1
	v_mfma_f32_16x16x32_bf16 v[116:119], v[132:135], v[188:191], 0
	v_mfma_f32_16x16x32_bf16 v[108:111], v[140:143], v[188:191], 0
	v_mfma_f32_16x16x32_bf16 v[100:103], v[132:135], v[180:183], 0
	v_mfma_f32_16x16x32_bf16 v[92:95], v[140:143], v[180:183], 0
	v_mfma_f32_16x16x32_bf16 v[84:87], v[132:135], v[172:175], 0
	v_mfma_f32_16x16x32_bf16 v[76:79], v[140:143], v[172:175], 0
	v_mfma_f32_16x16x32_bf16 v[72:75], v[132:135], v[164:167], 0
	v_mfma_f32_16x16x32_bf16 v[68:71], v[140:143], v[164:167], 0
	v_mfma_f32_16x16x32_bf16 v[116:119], v[136:139], v[192:195], v[116:119]
	v_mfma_f32_16x16x32_bf16 v[108:111], v[144:147], v[192:195], v[108:111]
	v_mfma_f32_16x16x32_bf16 v[100:103], v[136:139], v[184:187], v[100:103]
	v_mfma_f32_16x16x32_bf16 v[92:95], v[144:147], v[184:187], v[92:95]
	v_mfma_f32_16x16x32_bf16 v[84:87], v[136:139], v[176:179], v[84:87]
	v_mfma_f32_16x16x32_bf16 v[76:79], v[144:147], v[176:179], v[76:79]
	v_mfma_f32_16x16x32_bf16 v[72:75], v[136:139], v[168:171], v[72:75]
	v_mfma_f32_16x16x32_bf16 v[68:71], v[144:147], v[168:171], v[68:71]
	s_setprio 0
	s_barrier
	s_mov_b32 m0, s34
	v_lshl_add_u64 v[218:219], s[50:51], 0, v[206:207]
	s_add_u32 s56, s50, 0x40000
	ds_read_b128 v[188:191], v232 offset:16384
	ds_read_b128 v[192:195], v232 offset:17408
	ds_read_b128 v[180:183], v232 offset:18432
	ds_read_b128 v[184:187], v232 offset:19456
	ds_read_b128 v[172:175], v232 offset:20480
	ds_read_b128 v[176:179], v232 offset:21504
	ds_read_b128 v[164:167], v232 offset:22528
	ds_read_b128 v[168:171], v232 offset:23552
	global_load_lds_dwordx4 v[218:219], off
	v_lshl_add_u64 v[220:221], s[50:51], 0, v[202:203]
	s_mov_b32 m0, s35
	s_addc_u32 s57, s51, 0
	global_load_lds_dwordx4 v[220:221], off
	v_lshl_add_u64 v[222:223], s[56:57], 0, v[206:207]
	s_mov_b32 m0, s58
	v_lshl_add_u64 v[224:225], s[54:55], 0, v[204:205]
	global_load_lds_dwordx4 v[222:223], off
	v_lshl_add_u64 v[222:223], s[56:57], 0, v[202:203]
	s_mov_b32 m0, s59
	s_mov_b64 s[56:57], -1
	global_load_lds_dwordx4 v[222:223], off
	v_lshl_add_u64 v[222:223], s[54:55], 0, v[208:209]
	s_mov_b32 m0, s25
	s_and_b64 vcc, exec, s[52:53]
	global_load_lds_dwordx4 v[222:223], off
	s_mov_b32 m0, s60
	s_nop 0
	global_load_lds_dwordx4 v[224:225], off
	s_cbranch_vccz .Lpk_inproj_163
	s_waitcnt vmcnt(8)
	s_mov_b64 s[56:57], 0

; #define PG8_STAGE(bufoff, gbase, voff) do { _Pragma("unroll") for (int _i = 0; _i < 2; ++_i) \
;         __builtin_amdgcn_global_load_lds((const unsigned*)((const char*)(gbase) + (voff)[_i]), (PG8_LAS unsigned*)(lds + (bufoff) + ldsw + _i * 8192), 16, 0, 0); } while (0)
; #define PG8_LDA(dst, b, h) do { _Pragma("unroll") for (int m = 0; m < 4; ++m) _Pragma("unroll") for (int k = 0; k < 2; ++k) dst[m][k] = *(const PG8_LAS bf16x8*)(lds + PG8_SA(b, h) + aoff + m * 2048 + k * 1024); } while (0)
; #define PG8_LDB(dst, b, h) do { _Pragma("unroll") for (int n = 0; n < 2; ++n) _Pragma("unroll") for (int k = 0; k < 2; ++k) dst[n][k] = *(const PG8_LAS bf16x8*)(lds + PG8_SB(b, h) + boff + n * 2048 + k * 1024); } while (0)
; #define PG8_WAIT_VR(relax) do { if (relax) asm volatile("s_waitcnt vmcnt(%0)" :: "n"(8 + Epi::NST) : "memory"); else asm volatile("s_waitcnt vmcnt(8)" ::: "memory"); } while (0)
; #define PG8_WAIT_L(n) asm volatile("s_waitcnt lgkmcnt(" #n ")" ::: "memory")
; #define PG8_BAR __builtin_amdgcn_s_barrier()
; #define PG8_SCHED __builtin_amdgcn_sched_barrier(0)
; template <class Epi, class Sched, bool ALIGN_EPI = false, bool SP2 = false, bool F8 = false, bool GATHER = false>
; __device__ __forceinline__ void gemm_phase(PG8_LAS unsigned char* lds, const Gemm g, const Sched& S, const Epi& E, const int tid_in) {
;     ...
;             const char* a2 = last ? nA : cA + (size_t)(t + 2) * kstep; const char* b2 = last ? nB : cB + (size_t)(t + 2) * kstep;
;             const char* a3 = a2 + kstep; const char* b3 = b2 + kstep;
;             if (last && has_next) S.a_ready(nxt);
;             const bool relax = SP2 && ALIGN_EPI && t == 0 && ui > 0;
;             if constexpr (SP2) {
;             PG8_LDB(B0, 0, 0); PG8_LDB(B1, 0, 1); PG8_SCHED; PG8_LDA(At, 0, 0); if (!relax) PG8_STAGE(PG8_SA(1, 1), a1 + hstepA, vA1c);
;             PG8_WAIT_VR(relax); PG8_WAIT_L(0); PG8_BAR; PG8_MMA(0, 0, At, B0); PG8_MMA(0, 1, At, B1); PG8_BAR; PG8_SCHED;
;             PG8_LDA(At, 0, 1); PG8_STAGE(PG8_SB(0, 0), b2, voffB); PG8_STAGE(PG8_SB(0, 1), b2 + hstep, voffB); PG8_STAGE(PG8_SA(0, 0), a2, vA0s);
.LBB0_725:
	s_xor_b64 s[52:53], s[50:51], -1
	s_add_u32 s50, s40, s48
	s_addc_u32 s51, s41, s49
	s_add_u32 s50, s50, 0x100
	s_addc_u32 s51, s51, 0
	s_add_u32 s56, s77, s48
	s_addc_u32 s57, s78, s49
	s_cmpk_eq_i32 s48, 0x700
	s_cselect_b32 s55, s37, s51
	s_cselect_b32 s54, s75, s50
	s_cselect_b32 s51, s23, s57
	s_cselect_b32 s50, s76, s56
	s_waitcnt lgkmcnt(0)
	s_barrier
	s_setprio 1
	s_waitcnt lgkmcnt(0)
	v_mfma_f32_16x16x32_bf16 v[128:131], v[148:151], v[188:191], v[128:131]
	v_mfma_f32_16x16x32_bf16 v[124:127], v[156:159], v[188:191], v[124:127]
	v_mfma_f32_16x16x32_bf16 v[120:123], v[148:151], v[180:183], v[120:123]
	v_mfma_f32_16x16x32_bf16 v[112:115], v[156:159], v[180:183], v[112:115]
	v_mfma_f32_16x16x32_bf16 v[104:107], v[148:151], v[172:175], v[104:107]
	v_mfma_f32_16x16x32_bf16 v[96:99], v[156:159], v[172:175], v[96:99]
	v_mfma_f32_16x16x32_bf16 v[88:91], v[148:151], v[164:167], v[88:91]
	v_mfma_f32_16x16x32_bf16 v[80:83], v[156:159], v[164:167], v[80:83]
	v_mfma_f32_16x16x32_bf16 v[128:131], v[152:155], v[192:195], v[128:131]
	v_mfma_f32_16x16x32_bf16 v[124:127], v[160:163], v[192:195], v[124:127]
	v_mfma_f32_16x16x32_bf16 v[120:123], v[152:155], v[184:187], v[120:123]
	v_mfma_f32_16x16x32_bf16 v[112:115], v[160:163], v[184:187], v[112:115]
	v_mfma_f32_16x16x32_bf16 v[104:107], v[152:155], v[176:179], v[104:107]
	v_mfma_f32_16x16x32_bf16 v[96:99], v[160:163], v[176:179], v[96:99]
	v_mfma_f32_16x16x32_bf16 v[88:91], v[152:155], v[168:171], v[88:91]
	v_mfma_f32_16x16x32_bf16 v[80:83], v[160:163], v[168:171], v[80:83]
	s_setprio 0
	s_setprio 1
	v_mfma_f32_16x16x32_bf16 v[116:119], v[132:135], v[188:191], v[116:119]
	v_mfma_f32_16x16x32_bf16 v[108:111], v[140:143], v[188:191], v[108:111]
	v_mfma_f32_16x16x32_bf16 v[100:103], v[132:135], v[180:183], v[100:103]
	v_mfma_f32_16x16x32_bf16 v[92:95], v[140:143], v[180:183], v[92:95]
	v_mfma_f32_16x16x32_bf16 v[84:87], v[132:135], v[172:175], v[84:87]
	v_mfma_f32_16x16x32_bf16 v[76:79], v[140:143], v[172:175], v[76:79]
	v_mfma_f32_16x16x32_bf16 v[72:75], v[132:135], v[164:167], v[72:75]
	v_mfma_f32_16x16x32_bf16 v[68:71], v[140:143], v[164:167], v[68:71]
	v_mfma_f32_16x16x32_bf16 v[116:119], v[136:139], v[192:195], v[116:119]
	v_mfma_f32_16x16x32_bf16 v[108:111], v[144:147], v[192:195], v[108:111]
	v_mfma_f32_16x16x32_bf16 v[100:103], v[136:139], v[184:187], v[100:103]
	v_mfma_f32_16x16x32_bf16 v[92:95], v[144:147], v[184:187], v[92:95]
	v_mfma_f32_16x16x32_bf16 v[84:87], v[136:139], v[176:179], v[84:87]
	v_mfma_f32_16x16x32_bf16 v[76:79], v[144:147], v[176:179], v[76:79]
	v_mfma_f32_16x16x32_bf16 v[72:75], v[136:139], v[168:171], v[72:75]
	v_mfma_f32_16x16x32_bf16 v[68:71], v[144:147], v[168:171], v[68:71]
	s_setprio 0
	s_barrier
	s_mov_b32 m0, s34
	v_lshl_add_u64 v[218:219], s[50:51], 0, v[206:207]
	s_add_u32 s56, s50, 0x40000
	ds_read_b128 v[188:191], v227 offset:16384
	ds_read_b128 v[192:195], v227 offset:17408
	ds_read_b128 v[180:183], v227 offset:18432
	ds_read_b128 v[184:187], v227 offset:19456
	ds_read_b128 v[172:175], v227 offset:20480
	ds_read_b128 v[176:179], v227 offset:21504
	ds_read_b128 v[164:167], v227 offset:22528
	ds_read_b128 v[168:171], v227 offset:23552
	global_load_lds_dwordx4 v[218:219], off
	v_lshl_add_u64 v[220:221], s[50:51], 0, v[202:203]
	s_mov_b32 m0, s35
	s_addc_u32 s57, s51, 0
	global_load_lds_dwordx4 v[220:221], off
	v_lshl_add_u64 v[222:223], s[56:57], 0, v[206:207]
	s_mov_b32 m0, s58
	v_lshl_add_u64 v[224:225], s[54:55], 0, v[204:205]
	global_load_lds_dwordx4 v[222:223], off
	v_lshl_add_u64 v[222:223], s[56:57], 0, v[202:203]
	s_mov_b32 m0, s59
	s_mov_b64 s[56:57], -1
	global_load_lds_dwordx4 v[222:223], off
	v_lshl_add_u64 v[222:223], s[54:55], 0, v[208:209]
	s_mov_b32 m0, s25
	s_and_b64 vcc, exec, s[52:53]
	global_load_lds_dwordx4 v[222:223], off
	s_mov_b32 m0, s60
	s_nop 0
	global_load_lds_dwordx4 v[224:225], off
	s_cbranch_vccz .LBB0_727
	s_waitcnt vmcnt(8)
	s_mov_b64 s[56:57], 0

; #define PG8_STAGE(bufoff, gbase, voff) do { _Pragma("unroll") for (int _i = 0; _i < 2; ++_i) \
;         __builtin_amdgcn_global_load_lds((const unsigned*)((const char*)(gbase) + (voff)[_i]), (PG8_LAS unsigned*)(lds + (bufoff) + ldsw + _i * 8192), 16, 0, 0); } while (0)
; #define PG8_LDA(dst, b, h) do { _Pragma("unroll") for (int m = 0; m < 4; ++m) _Pragma("unroll") for (int k = 0; k < 2; ++k) dst[m][k] = *(const PG8_LAS bf16x8*)(lds + PG8_SA(b, h) + aoff + m * 2048 + k * 1024); } while (0)
; #define PG8_LDB(dst, b, h) do { _Pragma("unroll") for (int n = 0; n < 2; ++n) _Pragma("unroll") for (int k = 0; k < 2; ++k) dst[n][k] = *(const PG8_LAS bf16x8*)(lds + PG8_SB(b, h) + boff + n * 2048 + k * 1024); } while (0)
; #define PG8_WAIT_VR(relax) do { if (relax) asm volatile("s_waitcnt vmcnt(%0)" :: "n"(8 + Epi::NST) : "memory"); else asm volatile("s_waitcnt vmcnt(8)" ::: "memory"); } while (0)
; #define PG8_WAIT_L(n) asm volatile("s_waitcnt lgkmcnt(" #n ")" ::: "memory")
; #define PG8_BAR __builtin_amdgcn_s_barrier()
; #define PG8_SCHED __builtin_amdgcn_sched_barrier(0)
; template <class Epi, class Sched, bool ALIGN_EPI = false, bool SP2 = false, bool F8 = false, bool GATHER = false>
; __device__ __forceinline__ void gemm_phase(PG8_LAS unsigned char* lds, const Gemm g, const Sched& S, const Epi& E, const int tid_in) {
;     ...
;             const char* a2 = last ? nA : cA + (size_t)(t + 2) * kstep; const char* b2 = last ? nB : cB + (size_t)(t + 2) * kstep;
;             const char* a3 = a2 + kstep; const char* b3 = b2 + kstep;
;             if (last && has_next) S.a_ready(nxt);
;             const bool relax = SP2 && ALIGN_EPI && t == 0 && ui > 0;
;             if constexpr (SP2) {
;             PG8_LDB(B0, 0, 0); PG8_LDB(B1, 0, 1); PG8_SCHED; PG8_LDA(At, 0, 0); if (!relax) PG8_STAGE(PG8_SA(1, 1), a1 + hstepA, vA1c);
;             PG8_WAIT_VR(relax); PG8_WAIT_L(0); PG8_BAR; PG8_MMA(0, 0, At, B0); PG8_MMA(0, 1, At, B1); PG8_BAR; PG8_SCHED;
;             PG8_LDA(At, 0, 1); PG8_STAGE(PG8_SB(0, 0), b2, voffB); PG8_STAGE(PG8_SB(0, 1), b2 + hstep, voffB); PG8_STAGE(PG8_SA(0, 0), a2, vA0s);
.Lpk_outproj_725:
	s_xor_b64 s[52:53], s[50:51], -1
	s_add_u32 s50, s40, s48
	s_addc_u32 s51, s41, s49
	s_add_u32 s50, s50, 0x100
	s_addc_u32 s51, s51, 0
	s_add_u32 s56, s77, s48
	s_addc_u32 s57, s78, s49
	s_cmpk_eq_i32 s48, 0x700
	s_cselect_b32 s55, s37, s51
	s_cselect_b32 s54, s75, s50
	s_cselect_b32 s51, s23, s57
	s_cselect_b32 s50, s76, s56
	s_waitcnt lgkmcnt(0)
	s_barrier
	s_setprio 1
	s_waitcnt lgkmcnt(0)
	v_mfma_f32_16x16x32_bf16 v[128:131], v[148:151], v[188:191], 0
	v_mfma_f32_16x16x32_bf16 v[124:127], v[156:159], v[188:191], 0
	v_mfma_f32_16x16x32_bf16 v[120:123], v[148:151], v[180:183], 0
	v_mfma_f32_16x16x32_bf16 v[112:115], v[156:159], v[180:183], 0
	v_mfma_f32_16x16x32_bf16 v[104:107], v[148:151], v[172:175], 0
	v_mfma_f32_16x16x32_bf16 v[96:99], v[156:159], v[172:175], 0
	v_mfma_f32_16x16x32_bf16 v[88:91], v[148:151], v[164:167], 0
	v_mfma_f32_16x16x32_bf16 v[80:83], v[156:159], v[164:167], 0
	v_mfma_f32_16x16x32_bf16 v[128:131], v[152:155], v[192:195], v[128:131]
	v_mfma_f32_16x16x32_bf16 v[124:127], v[160:163], v[192:195], v[124:127]
	v_mfma_f32_16x16x32_bf16 v[120:123], v[152:155], v[184:187], v[120:123]
	v_mfma_f32_16x16x32_bf16 v[112:115], v[160:163], v[184:187], v[112:115]
	v_mfma_f32_16x16x32_bf16 v[104:107], v[152:155], v[176:179], v[104:107]
	v_mfma_f32_16x16x32_bf16 v[96:99], v[160:163], v[176:179], v[96:99]
	v_mfma_f32_16x16x32_bf16 v[88:91], v[152:155], v[168:171], v[88:91]
	v_mfma_f32_16x16x32_bf16 v[80:83], v[160:163], v[168:171], v[80:83]
	s_setprio 0
	s_setprio 1
	v_mfma_f32_16x16x32_bf16 v[116:119], v[132:135], v[188:191], 0
	v_mfma_f32_16x16x32_bf16 v[108:111], v[140:143], v[188:191], 0
	v_mfma_f32_16x16x32_bf16 v[100:103], v[132:135], v[180:183], 0
	v_mfma_f32_16x16x32_bf16 v[92:95], v[140:143], v[180:183], 0
	v_mfma_f32_16x16x32_bf16 v[84:87], v[132:135], v[172:175], 0
	v_mfma_f32_16x16x32_bf16 v[76:79], v[140:143], v[172:175], 0
	v_mfma_f32_16x16x32_bf16 v[72:75], v[132:135], v[164:167], 0
	v_mfma_f32_16x16x32_bf16 v[68:71], v[140:143], v[164:167], 0
	v_mfma_f32_16x16x32_bf16 v[116:119], v[136:139], v[192:195], v[116:119]
	v_mfma_f32_16x16x32_bf16 v[108:111], v[144:147], v[192:195], v[108:111]
	v_mfma_f32_16x16x32_bf16 v[100:103], v[136:139], v[184:187], v[100:103]
	v_mfma_f32_16x16x32_bf16 v[92:95], v[144:147], v[184:187], v[92:95]
	v_mfma_f32_16x16x32_bf16 v[84:87], v[136:139], v[176:179], v[84:87]
	v_mfma_f32_16x16x32_bf16 v[76:79], v[144:147], v[176:179], v[76:79]
	v_mfma_f32_16x16x32_bf16 v[72:75], v[136:139], v[168:171], v[72:75]
	v_mfma_f32_16x16x32_bf16 v[68:71], v[144:147], v[168:171], v[68:71]
	s_setprio 0
	s_barrier
	s_mov_b32 m0, s34
	v_lshl_add_u64 v[218:219], s[50:51], 0, v[206:207]
	s_add_u32 s56, s50, 0x40000
	ds_read_b128 v[188:191], v227 offset:16384
	ds_read_b128 v[192:195], v227 offset:17408
	ds_read_b128 v[180:183], v227 offset:18432
	ds_read_b128 v[184:187], v227 offset:19456
	ds_read_b128 v[172:175], v227 offset:20480
	ds_read_b128 v[176:179], v227 offset:21504
	ds_read_b128 v[164:167], v227 offset:22528
	ds_read_b128 v[168:171], v227 offset:23552
	global_load_lds_dwordx4 v[218:219], off
	v_lshl_add_u64 v[220:221], s[50:51], 0, v[202:203]
	s_mov_b32 m0, s35
	s_addc_u32 s57, s51, 0
	global_load_lds_dwordx4 v[220:221], off
	v_lshl_add_u64 v[222:223], s[56:57], 0, v[206:207]
	s_mov_b32 m0, s58
	v_lshl_add_u64 v[224:225], s[54:55], 0, v[204:205]
	global_load_lds_dwordx4 v[222:223], off
	v_lshl_add_u64 v[222:223], s[56:57], 0, v[202:203]
	s_mov_b32 m0, s59
	s_mov_b64 s[56:57], -1
	global_load_lds_dwordx4 v[222:223], off
	v_lshl_add_u64 v[222:223], s[54:55], 0, v[208:209]
	s_mov_b32 m0, s25
	s_and_b64 vcc, exec, s[52:53]
	global_load_lds_dwordx4 v[222:223], off
	s_mov_b32 m0, s60
	s_nop 0
	global_load_lds_dwordx4 v[224:225], off
	s_cbranch_vccz .Lpk_outproj_727
	s_waitcnt vmcnt(8)
	s_mov_b64 s[56:57], 0

; #define PG8_STAGE(bufoff, gbase, voff) do { _Pragma("unroll") for (int _i = 0; _i < 2; ++_i) \
;         __builtin_amdgcn_global_load_lds((const unsigned*)((const char*)(gbase) + (voff)[_i]), (PG8_LAS unsigned*)(lds + (bufoff) + ldsw + _i * 8192), 16, 0, 0); } while (0)
; #define PG8_LDA(dst, b, h) do { _Pragma("unroll") for (int m = 0; m < 4; ++m) _Pragma("unroll") for (int k = 0; k < 2; ++k) dst[m][k] = *(const PG8_LAS bf16x8*)(lds + PG8_SA(b, h) + aoff + m * 2048 + k * 1024); } while (0)
; #define PG8_WAIT_V(n) asm volatile("s_waitcnt vmcnt(" #n ")" ::: "memory")
; #define PG8_WAIT_VR(relax) do { if (relax) asm volatile("s_waitcnt vmcnt(%0)" :: "n"(8 + Epi::NST) : "memory"); else asm volatile("s_waitcnt vmcnt(8)" ::: "memory"); } while (0)
; #define PG8_WAIT_L(n) asm volatile("s_waitcnt lgkmcnt(" #n ")" ::: "memory")
; #define PG8_BAR __builtin_amdgcn_s_barrier()
; #define PG8_SCHED __builtin_amdgcn_sched_barrier(0)
; template <class Epi, class Sched, bool ALIGN_EPI = false, bool SP2 = false, bool F8 = false, bool GATHER = false>
; __device__ __forceinline__ void gemm_phase(PG8_LAS unsigned char* lds, const Gemm g, const Sched& S, const Epi& E, const int tid_in) {
;     ...
;         for (int t = 0; t < nt; t += 2) {
;     ...
;             PG8_WAIT_VR(relax); PG8_WAIT_L(0); PG8_BAR; PG8_MMA(0, 0, At, B0); PG8_MMA(0, 1, At, B1); PG8_BAR; PG8_SCHED;
;             PG8_LDA(At, 1, 1); PG8_STAGE(PG8_SB(1, 0), b3, voffB); PG8_STAGE(PG8_SB(1, 1), b3 + hstep, voffB); PG8_STAGE(PG8_SA(1, 0), a3, vA0s);
;             PG8_WAIT_V(8); PG8_WAIT_L(0); PG8_BAR; PG8_MMA(1, 0, At, B0); PG8_MMA(1, 1, At, B1); PG8_BAR; PG8_SCHED;
.LBB0_1001:
	v_mov_b32_e32 v223, v16
	v_mov_b32_e32 v221, v16
	v_lshl_add_u64 v[196:197], s[62:63], 0, v[222:223]
	v_lshl_add_u64 v[220:221], s[62:63], 0, v[220:221]
	s_waitcnt lgkmcnt(0)
	s_barrier
	s_setprio 1
	s_waitcnt lgkmcnt(0)
	v_mfma_f32_16x16x128_f8f6f4 v[192:195], v[26:33], v[58:65], v[192:195]
	v_mfma_f32_16x16x128_f8f6f4 v[188:191], v[18:25], v[58:65], v[188:191]
	v_mfma_f32_16x16x128_f8f6f4 v[176:179], v[26:33], v[50:57], v[176:179]
	v_mfma_f32_16x16x128_f8f6f4 v[172:175], v[18:25], v[50:57], v[172:175]
	v_mfma_f32_16x16x128_f8f6f4 v[160:163], v[26:33], v[42:49], v[160:163]
	v_mfma_f32_16x16x128_f8f6f4 v[156:159], v[18:25], v[42:49], v[156:159]
	v_mfma_f32_16x16x128_f8f6f4 v[144:147], v[26:33], v[34:41], v[144:147]
	v_mfma_f32_16x16x128_f8f6f4 v[140:143], v[18:25], v[34:41], v[140:143]
	s_setprio 0
	s_setprio 1
	v_mfma_f32_16x16x128_f8f6f4 v[184:187], v[8:15], v[58:65], v[184:187]
	v_mfma_f32_16x16x128_f8f6f4 v[180:183], v[0:7], v[58:65], v[180:183]
	v_mfma_f32_16x16x128_f8f6f4 v[168:171], v[8:15], v[50:57], v[168:171]
	v_mfma_f32_16x16x128_f8f6f4 v[164:167], v[0:7], v[50:57], v[164:167]
	v_mfma_f32_16x16x128_f8f6f4 v[152:155], v[8:15], v[42:49], v[152:155]
	v_mfma_f32_16x16x128_f8f6f4 v[148:151], v[0:7], v[42:49], v[148:151]
	v_mfma_f32_16x16x128_f8f6f4 v[136:139], v[8:15], v[34:41], v[136:139]
	v_mfma_f32_16x16x128_f8f6f4 v[132:135], v[0:7], v[34:41], v[132:135]
	s_setprio 0
	s_barrier
	s_mov_b32 m0, s84
	v_lshl_add_u64 v[222:223], v[224:225], 0, s[6:7]
	s_add_u32 s42, s60, 0x20080
	ds_read_b128 v[34:37], v231 offset:49152
	ds_read_b128 v[38:41], v231 offset:50176
	ds_read_b128 v[42:45], v231 offset:51200
	ds_read_b128 v[46:49], v231 offset:52224
	ds_read_b128 v[50:53], v231 offset:53248
	ds_read_b128 v[54:57], v231 offset:54272
	ds_read_b128 v[58:61], v231 offset:55296
	ds_read_b128 v[62:65], v231 offset:56320
	global_load_lds_dwordx4 v[222:223], off
	v_lshl_add_u64 v[222:223], v[226:227], 0, s[6:7]
	s_mov_b32 m0, s85
	s_addc_u32 s43, s61, 0
	global_load_lds_dwordx4 v[222:223], off
	v_lshl_add_u64 v[222:223], s[42:43], 0, v[202:203]
	s_mov_b32 m0, s88
	v_lshl_add_u64 v[196:197], v[196:197], 0, s[6:7]
	global_load_lds_dwordx4 v[222:223], off
	v_lshl_add_u64 v[222:223], s[42:43], 0, v[204:205]
	s_mov_b32 m0, s89
	s_nop 0
	global_load_lds_dwordx4 v[222:223], off
	s_mov_b32 m0, s86
	s_nop 0
	global_load_lds_dwordx4 v[196:197], off
	v_lshl_add_u64 v[196:197], v[220:221], 0, s[6:7]
	s_mov_b32 m0, s87
	s_nop 0
	global_load_lds_dwordx4 v[196:197], off
	s_waitcnt vmcnt(8)
	s_waitcnt lgkmcnt(0)
	s_barrier
	s_setprio 1
	s_waitcnt lgkmcnt(0)
	v_mfma_f32_16x16x128_f8f6f4 v[128:131], v[26:33], v[34:41], v[128:131]
	v_mfma_f32_16x16x128_f8f6f4 v[124:127], v[18:25], v[34:41], v[124:127]
	v_mfma_f32_16x16x128_f8f6f4 v[112:115], v[26:33], v[42:49], v[112:115]
	v_mfma_f32_16x16x128_f8f6f4 v[108:111], v[18:25], v[42:49], v[108:111]
	v_mfma_f32_16x16x128_f8f6f4 v[96:99], v[26:33], v[50:57], v[96:99]
	v_mfma_f32_16x16x128_f8f6f4 v[92:95], v[18:25], v[50:57], v[92:95]
	v_mfma_f32_16x16x128_f8f6f4 v[80:83], v[26:33], v[58:65], v[80:83]
	v_mfma_f32_16x16x128_f8f6f4 v[76:79], v[18:25], v[58:65], v[76:79]
	s_setprio 0
	s_setprio 1
	v_mfma_f32_16x16x128_f8f6f4 v[120:123], v[8:15], v[34:41], v[120:123]
	v_mfma_f32_16x16x128_f8f6f4 v[116:119], v[0:7], v[34:41], v[116:119]
	v_mfma_f32_16x16x128_f8f6f4 v[104:107], v[8:15], v[42:49], v[104:107]
	v_mfma_f32_16x16x128_f8f6f4 v[100:103], v[0:7], v[42:49], v[100:103]
	v_mfma_f32_16x16x128_f8f6f4 v[88:91], v[8:15], v[50:57], v[88:91]
	v_mfma_f32_16x16x128_f8f6f4 v[84:87], v[0:7], v[50:57], v[84:87]
	v_mfma_f32_16x16x128_f8f6f4 v[72:75], v[8:15], v[58:65], v[72:75]
	v_mfma_f32_16x16x128_f8f6f4 v[68:71], v[0:7], v[58:65], v[68:71]
	s_setprio 0
	s_barrier
	s_add_i32 s55, s55, 2
	s_add_u32 s36, s36, 0x100
	s_addc_u32 s37, s37, 0
	s_cmp_gt_u32 s55, 5
	s_cbranch_scc1 .LBB0_1016

; #define PG8_STAGE(bufoff, gbase, voff) do { _Pragma("unroll") for (int _i = 0; _i < 2; ++_i) \
;         __builtin_amdgcn_global_load_lds((const unsigned*)((const char*)(gbase) + (voff)[_i]), (PG8_LAS unsigned*)(lds + (bufoff) + ldsw + _i * 8192), 16, 0, 0); } while (0)
; #define PG8_LDA(dst, b, h) do { _Pragma("unroll") for (int m = 0; m < 4; ++m) _Pragma("unroll") for (int k = 0; k < 2; ++k) dst[m][k] = *(const PG8_LAS bf16x8*)(lds + PG8_SA(b, h) + aoff + m * 2048 + k * 1024); } while (0)
; #define PG8_LDB(dst, b, h) do { _Pragma("unroll") for (int n = 0; n < 2; ++n) _Pragma("unroll") for (int k = 0; k < 2; ++k) dst[n][k] = *(const PG8_LAS bf16x8*)(lds + PG8_SB(b, h) + boff + n * 2048 + k * 1024); } while (0)
; #define PG8_WAIT_VR(relax) do { if (relax) asm volatile("s_waitcnt vmcnt(%0)" :: "n"(8 + Epi::NST) : "memory"); else asm volatile("s_waitcnt vmcnt(8)" ::: "memory"); } while (0)
; template <class Epi, class Sched, bool ALIGN_EPI = false, bool SP2 = false, bool F8 = false, bool GATHER = false>
; __device__ __forceinline__ void gemm_phase(PG8_LAS unsigned char* lds, const Gemm g, const Sched& S, const Epi& E, const int tid_in) {
;     ...
;                 if (last) { vA0s[0] = ga_nxt[0][0]; vA0s[1] = ga_nxt[0][1]; vA1s[0] = ga_nxt[1][0]; vA1s[1] = ga_nxt[1][1]; }
;                 else { vA0s[0] = ga_cur[0][0]; vA0s[1] = ga_cur[0][1]; vA1s[0] = ga_cur[1][0]; vA1s[1] = ga_cur[1][1]; }
;                 vA1c[0] = ga_cur[1][0]; vA1c[1] = ga_cur[1][1];
;             } else { vA0s[0] = vA1s[0] = voffA[0]; vA0s[1] = vA1s[1] = voffA[1]; }
;             const char* a1 = cA + (size_t)(t + 1) * kstep;
;             const char* a2 = last ? nA : cA + (size_t)(t + 2) * kstep; const char* b2 = last ? nB : cB + (size_t)(t + 2) * kstep;
;             const char* a3 = a2 + kstep; const char* b3 = b2 + kstep;
;             if (last && has_next) S.a_ready(nxt);
;             const bool relax = SP2 && ALIGN_EPI && t == 0 && ui > 0;
;             if constexpr (SP2) {
;             PG8_LDB(B0, 0, 0); PG8_LDB(B1, 0, 1); PG8_SCHED; PG8_LDA(At, 0, 0); if (!relax) PG8_STAGE(PG8_SA(1, 1), a1 + hstepA, vA1c);
;             PG8_WAIT_VR(relax); PG8_WAIT_L(0); PG8_BAR; PG8_MMA(0, 0, At, B0); PG8_MMA(0, 1, At, B1); PG8_BAR; PG8_SCHED;
;             PG8_LDA(At, 0, 1); PG8_STAGE(PG8_SB(0, 0), b2, voffB); PG8_STAGE(PG8_SB(0, 1), b2 + hstep, voffB); PG8_STAGE(PG8_SA(0, 0), a2, vA0s);
.LBB0_1008:
	s_xor_b64 s[64:65], s[42:43], -1
	s_add_u32 s42, s16, s36
	s_addc_u32 s43, s17, s37
	s_add_u32 s62, s42, 0xcf000100
	s_addc_u32 s63, s43, 0
	s_add_u32 s66, s35, s36
	s_addc_u32 s67, s53, s37
	s_cmpk_eq_i32 s36, 0x300
	s_cselect_b64 s[42:43], -1, 0
	s_and_b64 s[60:61], s[42:43], exec
	v_cndmask_b32_e64 v220, v210, v234, s[42:43]
	v_cndmask_b32_e64 v222, v208, v215, s[42:43]
	s_cselect_b32 s63, s31, s63
	s_cselect_b32 s62, s30, s62
	s_cselect_b32 s61, s3, s67
	s_cselect_b32 s60, s34, s66
	s_waitcnt lgkmcnt(0)
	s_barrier
	s_setprio 1
	s_waitcnt lgkmcnt(0)
	v_mfma_f32_16x16x128_f8f6f4 v[192:195], v[26:33], v[58:65], v[192:195]
	v_mfma_f32_16x16x128_f8f6f4 v[188:191], v[18:25], v[58:65], v[188:191]
	v_mfma_f32_16x16x128_f8f6f4 v[176:179], v[26:33], v[50:57], v[176:179]
	v_mfma_f32_16x16x128_f8f6f4 v[172:175], v[18:25], v[50:57], v[172:175]
	v_mfma_f32_16x16x128_f8f6f4 v[160:163], v[26:33], v[42:49], v[160:163]
	v_mfma_f32_16x16x128_f8f6f4 v[156:159], v[18:25], v[42:49], v[156:159]
	v_mfma_f32_16x16x128_f8f6f4 v[144:147], v[26:33], v[34:41], v[144:147]
	v_mfma_f32_16x16x128_f8f6f4 v[140:143], v[18:25], v[34:41], v[140:143]
	s_setprio 0
	s_setprio 1
	v_mfma_f32_16x16x128_f8f6f4 v[184:187], v[8:15], v[58:65], v[184:187]
	v_mfma_f32_16x16x128_f8f6f4 v[180:183], v[0:7], v[58:65], v[180:183]
	v_mfma_f32_16x16x128_f8f6f4 v[168:171], v[8:15], v[50:57], v[168:171]
	v_mfma_f32_16x16x128_f8f6f4 v[164:167], v[0:7], v[50:57], v[164:167]
	v_mfma_f32_16x16x128_f8f6f4 v[152:155], v[8:15], v[42:49], v[152:155]
	v_mfma_f32_16x16x128_f8f6f4 v[148:151], v[0:7], v[42:49], v[148:151]
	v_mfma_f32_16x16x128_f8f6f4 v[136:139], v[8:15], v[34:41], v[136:139]
	v_mfma_f32_16x16x128_f8f6f4 v[132:135], v[0:7], v[34:41], v[132:135]
	s_setprio 0
	s_barrier
	s_mov_b32 m0, s77
	v_lshl_add_u64 v[224:225], s[60:61], 0, v[202:203]
	s_add_u32 s66, s60, 0x20000
	ds_read_b128 v[58:61], v231 offset:16384
	ds_read_b128 v[62:65], v231 offset:17408
	ds_read_b128 v[50:53], v231 offset:18432
	ds_read_b128 v[54:57], v231 offset:19456
	ds_read_b128 v[42:45], v231 offset:20480
	ds_read_b128 v[46:49], v231 offset:21504
	ds_read_b128 v[34:37], v231 offset:22528
	ds_read_b128 v[38:41], v231 offset:23552
	global_load_lds_dwordx4 v[224:225], off
	v_lshl_add_u64 v[226:227], s[60:61], 0, v[204:205]
	s_mov_b32 m0, s78
	s_addc_u32 s67, s61, 0
	global_load_lds_dwordx4 v[226:227], off
	v_lshl_add_u64 v[196:197], s[66:67], 0, v[202:203]
	s_mov_b32 m0, s79
	s_and_b64 vcc, exec, s[64:65]
	global_load_lds_dwordx4 v[196:197], off
	v_lshl_add_u64 v[196:197], s[66:67], 0, v[204:205]
	s_mov_b32 m0, s80
	s_mov_b64 s[66:67], -1
	global_load_lds_dwordx4 v[196:197], off
	s_mov_b32 m0, s76
	s_nop 0
	global_load_lds_dwordx4 v222, s[62:63]
	s_mov_b32 m0, s81
	s_nop 0
	global_load_lds_dwordx4 v220, s[62:63]
	s_cbranch_vccz .LBB0_1010
	s_waitcnt vmcnt(8)
	s_mov_b64 s[66:67], 0

; #define PG8_STAGE(bufoff, gbase, voff) do { _Pragma("unroll") for (int _i = 0; _i < 2; ++_i) \
;         __builtin_amdgcn_global_load_lds((const unsigned*)((const char*)(gbase) + (voff)[_i]), (PG8_LAS unsigned*)(lds + (bufoff) + ldsw + _i * 8192), 16, 0, 0); } while (0)
; #define PG8_LDA(dst, b, h) do { _Pragma("unroll") for (int m = 0; m < 4; ++m) _Pragma("unroll") for (int k = 0; k < 2; ++k) dst[m][k] = *(const PG8_LAS bf16x8*)(lds + PG8_SA(b, h) + aoff + m * 2048 + k * 1024); } while (0)
; #define PG8_WAIT_L(n) asm volatile("s_waitcnt lgkmcnt(" #n ")" ::: "memory")
; #define PG8_BAR __builtin_amdgcn_s_barrier()
; template <class Epi, class Sched, bool ALIGN_EPI = false, bool SP2 = false, bool F8 = false, bool GATHER = false>
; __device__ __forceinline__ void gemm_phase(PG8_LAS unsigned char* lds, const Gemm g, const Sched& S, const Epi& E, const int tid_in) {
;     ...
;                 if (last) { vA0s[0] = ga_nxt[0][0]; vA0s[1] = ga_nxt[0][1]; vA1s[0] = ga_nxt[1][0]; vA1s[1] = ga_nxt[1][1]; }
;                 else { vA0s[0] = ga_cur[0][0]; vA0s[1] = ga_cur[0][1]; vA1s[0] = ga_cur[1][0]; vA1s[1] = ga_cur[1][1]; }
;                 vA1c[0] = ga_cur[1][0]; vA1c[1] = ga_cur[1][1];
;             } else { vA0s[0] = vA1s[0] = voffA[0]; vA0s[1] = vA1s[1] = voffA[1]; }
;             const char* a1 = cA + (size_t)(t + 1) * kstep;
;             const char* a2 = last ? nA : cA + (size_t)(t + 2) * kstep; const char* b2 = last ? nB : cB + (size_t)(t + 2) * kstep;
;             const char* a3 = a2 + kstep; const char* b3 = b2 + kstep;
;             if (last && has_next) S.a_ready(nxt);
;             const bool relax = SP2 && ALIGN_EPI && t == 0 && ui > 0;
;             if constexpr (SP2) {
;             PG8_LDB(B0, 0, 0); PG8_LDB(B1, 0, 1); PG8_SCHED; PG8_LDA(At, 0, 0); if (!relax) PG8_STAGE(PG8_SA(1, 1), a1 + hstepA, vA1c);
;             PG8_WAIT_VR(relax); PG8_WAIT_L(0); PG8_BAR; PG8_MMA(0, 0, At, B0); PG8_MMA(0, 1, At, B1); PG8_BAR; PG8_SCHED;
;             PG8_LDA(At, 0, 1); PG8_STAGE(PG8_SB(0, 0), b2, voffB); PG8_STAGE(PG8_SB(0, 1), b2 + hstep, voffB); PG8_STAGE(PG8_SA(0, 0), a2, vA0s);
;             PG8_WAIT_VR(relax); PG8_WAIT_L(0); PG8_BAR; PG8_MMA(1, 0, At, B0); PG8_MMA(1, 1, At, B1); PG8_BAR; PG8_SCHED;
;             PG8_LDB(B0, 1, 0); PG8_LDB(B1, 1, 1); PG8_SCHED; PG8_LDA(At, 1, 0); PG8_STAGE(PG8_SA(0, 1), a2 + hstepA, vA1s);
.LBB0_1012:
	v_cndmask_b32_e64 v196, v214, v232, s[42:43]
	v_cndmask_b32_e64 v197, v212, v213, s[42:43]
	s_waitcnt lgkmcnt(0)
	s_barrier
	s_setprio 1
	s_waitcnt lgkmcnt(0)
	v_mfma_f32_16x16x128_f8f6f4 v[128:131], v[26:33], v[58:65], v[128:131]
	v_mfma_f32_16x16x128_f8f6f4 v[124:127], v[18:25], v[58:65], v[124:127]
	v_mfma_f32_16x16x128_f8f6f4 v[112:115], v[26:33], v[50:57], v[112:115]
	v_mfma_f32_16x16x128_f8f6f4 v[108:111], v[18:25], v[50:57], v[108:111]
	v_mfma_f32_16x16x128_f8f6f4 v[96:99], v[26:33], v[42:49], v[96:99]
	v_mfma_f32_16x16x128_f8f6f4 v[92:95], v[18:25], v[42:49], v[92:95]
	v_mfma_f32_16x16x128_f8f6f4 v[80:83], v[26:33], v[34:41], v[80:83]
	v_mfma_f32_16x16x128_f8f6f4 v[76:79], v[18:25], v[34:41], v[76:79]
	s_setprio 0
	s_setprio 1
	v_mfma_f32_16x16x128_f8f6f4 v[120:123], v[8:15], v[58:65], v[120:123]
	v_mfma_f32_16x16x128_f8f6f4 v[116:119], v[0:7], v[58:65], v[116:119]
	v_mfma_f32_16x16x128_f8f6f4 v[104:107], v[8:15], v[50:57], v[104:107]
	v_mfma_f32_16x16x128_f8f6f4 v[100:103], v[0:7], v[50:57], v[100:103]
	v_mfma_f32_16x16x128_f8f6f4 v[88:91], v[8:15], v[42:49], v[88:91]
	v_mfma_f32_16x16x128_f8f6f4 v[84:87], v[0:7], v[42:49], v[84:87]
	v_mfma_f32_16x16x128_f8f6f4 v[72:75], v[8:15], v[34:41], v[72:75]
	v_mfma_f32_16x16x128_f8f6f4 v[68:71], v[0:7], v[34:41], v[68:71]
	s_setprio 0
	s_barrier
	v_add_u32_e32 v0, 0x18000, v249
	v_add_u32_e32 v4, 0x1c000, v249
	ds_read_b128 v[26:29], v0
	ds_read_b128 v[30:33], v0 offset:1024
	ds_read_b128 v[18:21], v0 offset:2048
	ds_read_b128 v[22:25], v0 offset:3072
	ds_read_b128 v[8:11], v4
	ds_read_b128 v[12:15], v4 offset:1024
	ds_read_b128 v[0:3], v4 offset:2048
	ds_read_b128 v[4:7], v4 offset:3072
	s_mov_b32 m0, s82
	ds_read_b128 v[58:61], v231 offset:32768
	ds_read_b128 v[62:65], v231 offset:33792
	ds_read_b128 v[50:53], v231 offset:34816
	ds_read_b128 v[54:57], v231 offset:35840
	ds_read_b128 v[42:45], v231 offset:36864
	ds_read_b128 v[46:49], v231 offset:37888
	ds_read_b128 v[34:37], v231 offset:38912
	ds_read_b128 v[38:41], v231 offset:39936
	global_load_lds_dwordx4 v197, s[62:63]
	s_mov_b32 m0, s83
	s_mov_b64 s[42:43], -1
	global_load_lds_dwordx4 v196, s[62:63]
	s_and_b64 vcc, exec, s[64:65]
	s_mov_b32 s66, s27
	s_mov_b32 s67, s24
	s_cbranch_vccz .LBB0_1014
	s_waitcnt vmcnt(8)
	s_mov_b64 s[42:43], 0

; #define PG8_STAGE(bufoff, gbase, voff) do { _Pragma("unroll") for (int _i = 0; _i < 2; ++_i) \
;         __builtin_amdgcn_global_load_lds((const unsigned*)((const char*)(gbase) + (voff)[_i]), (PG8_LAS unsigned*)(lds + (bufoff) + ldsw + _i * 8192), 16, 0, 0); } while (0)
; #define PG8_LDA(dst, b, h) do { _Pragma("unroll") for (int m = 0; m < 4; ++m) _Pragma("unroll") for (int k = 0; k < 2; ++k) dst[m][k] = *(const PG8_LAS bf16x8*)(lds + PG8_SA(b, h) + aoff + m * 2048 + k * 1024); } while (0)
; #define PG8_LDB(dst, b, h) do { _Pragma("unroll") for (int n = 0; n < 2; ++n) _Pragma("unroll") for (int k = 0; k < 2; ++k) dst[n][k] = *(const PG8_LAS bf16x8*)(lds + PG8_SB(b, h) + boff + n * 2048 + k * 1024); } while (0)
; #define PG8_WAIT_VR(relax) do { if (relax) asm volatile("s_waitcnt vmcnt(%0)" :: "n"(8 + Epi::NST) : "memory"); else asm volatile("s_waitcnt vmcnt(8)" ::: "memory"); } while (0)
; template <class Epi, class Sched, bool ALIGN_EPI = false, bool SP2 = false, bool F8 = false, bool GATHER = false>
; __device__ __forceinline__ void gemm_phase(PG8_LAS unsigned char* lds, const Gemm g, const Sched& S, const Epi& E, const int tid_in) {
;     ...
;                 if (last) { vA0s[0] = ga_nxt[0][0]; vA0s[1] = ga_nxt[0][1]; vA1s[0] = ga_nxt[1][0]; vA1s[1] = ga_nxt[1][1]; }
;                 else { vA0s[0] = ga_cur[0][0]; vA0s[1] = ga_cur[0][1]; vA1s[0] = ga_cur[1][0]; vA1s[1] = ga_cur[1][1]; }
;                 vA1c[0] = ga_cur[1][0]; vA1c[1] = ga_cur[1][1];
;             } else { vA0s[0] = vA1s[0] = voffA[0]; vA0s[1] = vA1s[1] = voffA[1]; }
;             const char* a1 = cA + (size_t)(t + 1) * kstep;
;             const char* a2 = last ? nA : cA + (size_t)(t + 2) * kstep; const char* b2 = last ? nB : cB + (size_t)(t + 2) * kstep;
;             const char* a3 = a2 + kstep; const char* b3 = b2 + kstep;
;             if (last && has_next) S.a_ready(nxt);
;             const bool relax = SP2 && ALIGN_EPI && t == 0 && ui > 0;
;             if constexpr (SP2) {
;             PG8_LDB(B0, 0, 0); PG8_LDB(B1, 0, 1); PG8_SCHED; PG8_LDA(At, 0, 0); if (!relax) PG8_STAGE(PG8_SA(1, 1), a1 + hstepA, vA1c);
;             PG8_WAIT_VR(relax); PG8_WAIT_L(0); PG8_BAR; PG8_MMA(0, 0, At, B0); PG8_MMA(0, 1, At, B1); PG8_BAR; PG8_SCHED;
;             PG8_LDA(At, 0, 1); PG8_STAGE(PG8_SB(0, 0), b2, voffB); PG8_STAGE(PG8_SB(0, 1), b2 + hstep, voffB); PG8_STAGE(PG8_SA(0, 0), a2, vA0s);
.Lpk_g1_1008:
	s_xor_b64 s[64:65], s[42:43], -1
	s_add_u32 s42, s16, s36
	s_addc_u32 s43, s17, s37
	s_add_u32 s62, s42, 0xcf000100
	s_addc_u32 s63, s43, 0
	s_add_u32 s66, s35, s36
	s_addc_u32 s67, s53, s37
	s_cmpk_eq_i32 s36, 0x300
	s_cselect_b64 s[42:43], -1, 0
	s_and_b64 s[60:61], s[42:43], exec
	v_cndmask_b32_e64 v220, v210, v234, s[42:43]
	v_cndmask_b32_e64 v222, v208, v215, s[42:43]
	s_cselect_b32 s63, s31, s63
	s_cselect_b32 s62, s30, s62
	s_cselect_b32 s61, s3, s67
	s_cselect_b32 s60, s34, s66
	s_waitcnt lgkmcnt(0)
	s_barrier
	s_setprio 1
	s_waitcnt lgkmcnt(0)
	v_mfma_f32_16x16x128_f8f6f4 v[192:195], v[26:33], v[58:65], 0
	v_mfma_f32_16x16x128_f8f6f4 v[188:191], v[18:25], v[58:65], 0
	v_mfma_f32_16x16x128_f8f6f4 v[176:179], v[26:33], v[50:57], 0
	v_mfma_f32_16x16x128_f8f6f4 v[172:175], v[18:25], v[50:57], 0
	v_mfma_f32_16x16x128_f8f6f4 v[160:163], v[26:33], v[42:49], 0
	v_mfma_f32_16x16x128_f8f6f4 v[156:159], v[18:25], v[42:49], 0
	v_mfma_f32_16x16x128_f8f6f4 v[144:147], v[26:33], v[34:41], 0
	v_mfma_f32_16x16x128_f8f6f4 v[140:143], v[18:25], v[34:41], 0
	s_setprio 0
	s_setprio 1
	v_mfma_f32_16x16x128_f8f6f4 v[184:187], v[8:15], v[58:65], 0
	v_mfma_f32_16x16x128_f8f6f4 v[180:183], v[0:7], v[58:65], 0
	v_mfma_f32_16x16x128_f8f6f4 v[168:171], v[8:15], v[50:57], 0
	v_mfma_f32_16x16x128_f8f6f4 v[164:167], v[0:7], v[50:57], 0
	v_mfma_f32_16x16x128_f8f6f4 v[152:155], v[8:15], v[42:49], 0
	v_mfma_f32_16x16x128_f8f6f4 v[148:151], v[0:7], v[42:49], 0
	v_mfma_f32_16x16x128_f8f6f4 v[136:139], v[8:15], v[34:41], 0
	v_mfma_f32_16x16x128_f8f6f4 v[132:135], v[0:7], v[34:41], 0
	s_setprio 0
	s_barrier
	s_mov_b32 m0, s77
	v_lshl_add_u64 v[224:225], s[60:61], 0, v[202:203]
	s_add_u32 s66, s60, 0x20000
	ds_read_b128 v[58:61], v231 offset:16384
	ds_read_b128 v[62:65], v231 offset:17408
	ds_read_b128 v[50:53], v231 offset:18432
	ds_read_b128 v[54:57], v231 offset:19456
	ds_read_b128 v[42:45], v231 offset:20480
	ds_read_b128 v[46:49], v231 offset:21504
	ds_read_b128 v[34:37], v231 offset:22528
	ds_read_b128 v[38:41], v231 offset:23552
	global_load_lds_dwordx4 v[224:225], off
	v_lshl_add_u64 v[226:227], s[60:61], 0, v[204:205]
	s_mov_b32 m0, s78
	s_addc_u32 s67, s61, 0
	global_load_lds_dwordx4 v[226:227], off
	v_lshl_add_u64 v[196:197], s[66:67], 0, v[202:203]
	s_mov_b32 m0, s79
	s_and_b64 vcc, exec, s[64:65]
	global_load_lds_dwordx4 v[196:197], off
	v_lshl_add_u64 v[196:197], s[66:67], 0, v[204:205]
	s_mov_b32 m0, s80
	s_mov_b64 s[66:67], -1
	global_load_lds_dwordx4 v[196:197], off
	s_mov_b32 m0, s76
	s_nop 0
	global_load_lds_dwordx4 v222, s[62:63]
	s_mov_b32 m0, s81
	s_nop 0
	global_load_lds_dwordx4 v220, s[62:63]
	s_cbranch_vccz .Lpk_g1_1010
	s_waitcnt vmcnt(8)
	s_mov_b64 s[66:67], 0

; #define PG8_STAGE(bufoff, gbase, voff) do { _Pragma("unroll") for (int _i = 0; _i < 2; ++_i) \
;         __builtin_amdgcn_global_load_lds((const unsigned*)((const char*)(gbase) + (voff)[_i]), (PG8_LAS unsigned*)(lds + (bufoff) + ldsw + _i * 8192), 16, 0, 0); } while (0)
; #define PG8_LDA(dst, b, h) do { _Pragma("unroll") for (int m = 0; m < 4; ++m) _Pragma("unroll") for (int k = 0; k < 2; ++k) dst[m][k] = *(const PG8_LAS bf16x8*)(lds + PG8_SA(b, h) + aoff + m * 2048 + k * 1024); } while (0)
; #define PG8_WAIT_L(n) asm volatile("s_waitcnt lgkmcnt(" #n ")" ::: "memory")
; #define PG8_BAR __builtin_amdgcn_s_barrier()
; template <class Epi, class Sched, bool ALIGN_EPI = false, bool SP2 = false, bool F8 = false, bool GATHER = false>
; __device__ __forceinline__ void gemm_phase(PG8_LAS unsigned char* lds, const Gemm g, const Sched& S, const Epi& E, const int tid_in) {
;     ...
;                 if (last) { vA0s[0] = ga_nxt[0][0]; vA0s[1] = ga_nxt[0][1]; vA1s[0] = ga_nxt[1][0]; vA1s[1] = ga_nxt[1][1]; }
;                 else { vA0s[0] = ga_cur[0][0]; vA0s[1] = ga_cur[0][1]; vA1s[0] = ga_cur[1][0]; vA1s[1] = ga_cur[1][1]; }
;                 vA1c[0] = ga_cur[1][0]; vA1c[1] = ga_cur[1][1];
;             } else { vA0s[0] = vA1s[0] = voffA[0]; vA0s[1] = vA1s[1] = voffA[1]; }
;             const char* a1 = cA + (size_t)(t + 1) * kstep;
;             const char* a2 = last ? nA : cA + (size_t)(t + 2) * kstep; const char* b2 = last ? nB : cB + (size_t)(t + 2) * kstep;
;             const char* a3 = a2 + kstep; const char* b3 = b2 + kstep;
;             if (last && has_next) S.a_ready(nxt);
;             const bool relax = SP2 && ALIGN_EPI && t == 0 && ui > 0;
;             if constexpr (SP2) {
;             PG8_LDB(B0, 0, 0); PG8_LDB(B1, 0, 1); PG8_SCHED; PG8_LDA(At, 0, 0); if (!relax) PG8_STAGE(PG8_SA(1, 1), a1 + hstepA, vA1c);
;             PG8_WAIT_VR(relax); PG8_WAIT_L(0); PG8_BAR; PG8_MMA(0, 0, At, B0); PG8_MMA(0, 1, At, B1); PG8_BAR; PG8_SCHED;
;             PG8_LDA(At, 0, 1); PG8_STAGE(PG8_SB(0, 0), b2, voffB); PG8_STAGE(PG8_SB(0, 1), b2 + hstep, voffB); PG8_STAGE(PG8_SA(0, 0), a2, vA0s);
;             PG8_WAIT_VR(relax); PG8_WAIT_L(0); PG8_BAR; PG8_MMA(1, 0, At, B0); PG8_MMA(1, 1, At, B1); PG8_BAR; PG8_SCHED;
;             PG8_LDB(B0, 1, 0); PG8_LDB(B1, 1, 1); PG8_SCHED; PG8_LDA(At, 1, 0); PG8_STAGE(PG8_SA(0, 1), a2 + hstepA, vA1s);
.Lpk_g1_1012:
	v_cndmask_b32_e64 v196, v214, v232, s[42:43]
	v_cndmask_b32_e64 v197, v212, v213, s[42:43]
	s_waitcnt lgkmcnt(0)
	s_barrier
	s_setprio 1
	s_waitcnt lgkmcnt(0)
	v_mfma_f32_16x16x128_f8f6f4 v[128:131], v[26:33], v[58:65], 0
	v_mfma_f32_16x16x128_f8f6f4 v[124:127], v[18:25], v[58:65], 0
	v_mfma_f32_16x16x128_f8f6f4 v[112:115], v[26:33], v[50:57], 0
	v_mfma_f32_16x16x128_f8f6f4 v[108:111], v[18:25], v[50:57], 0
	v_mfma_f32_16x16x128_f8f6f4 v[96:99], v[26:33], v[42:49], 0
	v_mfma_f32_16x16x128_f8f6f4 v[92:95], v[18:25], v[42:49], 0
	v_mfma_f32_16x16x128_f8f6f4 v[80:83], v[26:33], v[34:41], 0
	v_mfma_f32_16x16x128_f8f6f4 v[76:79], v[18:25], v[34:41], 0
	s_setprio 0
	s_setprio 1
	v_mfma_f32_16x16x128_f8f6f4 v[120:123], v[8:15], v[58:65], 0
	v_mfma_f32_16x16x128_f8f6f4 v[116:119], v[0:7], v[58:65], 0
	v_mfma_f32_16x16x128_f8f6f4 v[104:107], v[8:15], v[50:57], 0
	v_mfma_f32_16x16x128_f8f6f4 v[100:103], v[0:7], v[50:57], 0
	v_mfma_f32_16x16x128_f8f6f4 v[88:91], v[8:15], v[42:49], 0
	v_mfma_f32_16x16x128_f8f6f4 v[84:87], v[0:7], v[42:49], 0
	v_mfma_f32_16x16x128_f8f6f4 v[72:75], v[8:15], v[34:41], 0
	v_mfma_f32_16x16x128_f8f6f4 v[68:71], v[0:7], v[34:41], 0
	s_setprio 0
	s_barrier
	v_add_u32_e32 v0, 0x18000, v249
	v_add_u32_e32 v4, 0x1c000, v249
	ds_read_b128 v[26:29], v0
	ds_read_b128 v[30:33], v0 offset:1024
	ds_read_b128 v[18:21], v0 offset:2048
	ds_read_b128 v[22:25], v0 offset:3072
	ds_read_b128 v[8:11], v4
	ds_read_b128 v[12:15], v4 offset:1024
	ds_read_b128 v[0:3], v4 offset:2048
	ds_read_b128 v[4:7], v4 offset:3072
	s_mov_b32 m0, s82
	ds_read_b128 v[58:61], v231 offset:32768
	ds_read_b128 v[62:65], v231 offset:33792
	ds_read_b128 v[50:53], v231 offset:34816
	ds_read_b128 v[54:57], v231 offset:35840
	ds_read_b128 v[42:45], v231 offset:36864
	ds_read_b128 v[46:49], v231 offset:37888
	ds_read_b128 v[34:37], v231 offset:38912
	ds_read_b128 v[38:41], v231 offset:39936
	global_load_lds_dwordx4 v197, s[62:63]
	s_mov_b32 m0, s83
	s_mov_b64 s[42:43], -1
	global_load_lds_dwordx4 v196, s[62:63]
	s_and_b64 vcc, exec, s[64:65]
	s_mov_b32 s66, s27
	s_mov_b32 s67, s24
	s_cbranch_vccz .Lpk_g1_1014
	s_waitcnt vmcnt(8)
	s_mov_b64 s[42:43], 0

; #define PG8_STAGE(bufoff, gbase, voff) do { _Pragma("unroll") for (int _i = 0; _i < 2; ++_i) \
;         __builtin_amdgcn_global_load_lds((const unsigned*)((const char*)(gbase) + (voff)[_i]), (PG8_LAS unsigned*)(lds + (bufoff) + ldsw + _i * 8192), 16, 0, 0); } while (0)
; #define PG8_LDA(dst, b, h) do { _Pragma("unroll") for (int m = 0; m < 4; ++m) _Pragma("unroll") for (int k = 0; k < 2; ++k) dst[m][k] = *(const PG8_LAS bf16x8*)(lds + PG8_SA(b, h) + aoff + m * 2048 + k * 1024); } while (0)
; #define PG8_LDB(dst, b, h) do { _Pragma("unroll") for (int n = 0; n < 2; ++n) _Pragma("unroll") for (int k = 0; k < 2; ++k) dst[n][k] = *(const PG8_LAS bf16x8*)(lds + PG8_SB(b, h) + boff + n * 2048 + k * 1024); } while (0)
; #define PG8_WAIT_VR(relax) do { if (relax) asm volatile("s_waitcnt vmcnt(%0)" :: "n"(8 + Epi::NST) : "memory"); else asm volatile("s_waitcnt vmcnt(8)" ::: "memory"); } while (0)
; #define PG8_WAIT_L(n) asm volatile("s_waitcnt lgkmcnt(" #n ")" ::: "memory")
; #define PG8_BAR __builtin_amdgcn_s_barrier()
; #define PG8_SCHED __builtin_amdgcn_sched_barrier(0)
; template <class Epi, class Sched, bool ALIGN_EPI = false, bool SP2 = false, bool F8 = false, bool GATHER = false>
; __device__ __forceinline__ void gemm_phase(PG8_LAS unsigned char* lds, const Gemm g, const Sched& S, const Epi& E, const int tid_in) {
;     ...
;             const char* a2 = last ? nA : cA + (size_t)(t + 2) * kstep; const char* b2 = last ? nB : cB + (size_t)(t + 2) * kstep;
;             const char* a3 = a2 + kstep; const char* b3 = b2 + kstep;
;             if (last && has_next) S.a_ready(nxt);
;             const bool relax = SP2 && ALIGN_EPI && t == 0 && ui > 0;
;             if constexpr (SP2) {
;             PG8_LDB(B0, 0, 0); PG8_LDB(B1, 0, 1); PG8_SCHED; PG8_LDA(At, 0, 0); if (!relax) PG8_STAGE(PG8_SA(1, 1), a1 + hstepA, vA1c);
;             PG8_WAIT_VR(relax); PG8_WAIT_L(0); PG8_BAR; PG8_MMA(0, 0, At, B0); PG8_MMA(0, 1, At, B1); PG8_BAR; PG8_SCHED;
;             PG8_LDA(At, 0, 1); PG8_STAGE(PG8_SB(0, 0), b2, voffB); PG8_STAGE(PG8_SB(0, 1), b2 + hstep, voffB); PG8_STAGE(PG8_SA(0, 0), a2, vA0s);
.LBB0_1114:
	s_xor_b64 s[64:65], s[62:63], -1
	s_add_u32 s62, s42, s60
	s_addc_u32 s63, s43, s61
	s_add_u32 s62, s62, 0x100
	s_addc_u32 s63, s63, 0
	s_add_u32 s72, s92, s60
	s_addc_u32 s73, s93, s61
	s_cmpk_eq_i32 s60, 0x300
	s_cselect_b32 s67, s3, s63
	s_cselect_b32 s66, s49, s62
	s_cselect_b32 s63, s37, s73
	s_cselect_b32 s62, s91, s72
	s_waitcnt lgkmcnt(0)
	s_barrier
	s_setprio 1
	s_waitcnt lgkmcnt(0)
	v_mfma_f32_16x16x128_f8f6f4 v[192:195], v[26:33], v[58:65], v[192:195]
	v_mfma_f32_16x16x128_f8f6f4 v[188:191], v[18:25], v[58:65], v[188:191]
	v_mfma_f32_16x16x128_f8f6f4 v[184:187], v[26:33], v[50:57], v[184:187]
	v_mfma_f32_16x16x128_f8f6f4 v[180:183], v[18:25], v[50:57], v[180:183]
	v_mfma_f32_16x16x128_f8f6f4 v[160:163], v[26:33], v[42:49], v[160:163]
	v_mfma_f32_16x16x128_f8f6f4 v[156:159], v[18:25], v[42:49], v[156:159]
	v_mfma_f32_16x16x128_f8f6f4 v[152:155], v[26:33], v[34:41], v[152:155]
	v_mfma_f32_16x16x128_f8f6f4 v[148:151], v[18:25], v[34:41], v[148:151]
	s_setprio 0
	s_setprio 1
	v_mfma_f32_16x16x128_f8f6f4 v[176:179], v[8:15], v[58:65], v[176:179]
	v_mfma_f32_16x16x128_f8f6f4 v[172:175], v[0:7], v[58:65], v[172:175]
	v_mfma_f32_16x16x128_f8f6f4 v[168:171], v[8:15], v[50:57], v[168:171]
	v_mfma_f32_16x16x128_f8f6f4 v[164:167], v[0:7], v[50:57], v[164:167]
	v_mfma_f32_16x16x128_f8f6f4 v[144:147], v[8:15], v[42:49], v[144:147]
	v_mfma_f32_16x16x128_f8f6f4 v[140:143], v[0:7], v[42:49], v[140:143]
	v_mfma_f32_16x16x128_f8f6f4 v[136:139], v[8:15], v[34:41], v[136:139]
	v_mfma_f32_16x16x128_f8f6f4 v[132:135], v[0:7], v[34:41], v[132:135]
	s_setprio 0
	s_barrier
	s_mov_b32 m0, s57
	v_lshl_add_u64 v[218:219], s[62:63], 0, v[204:205]
	s_add_u32 s72, s62, 0x20000
	ds_read_b128 v[58:61], v242 offset:16384
	ds_read_b128 v[62:65], v242 offset:17408
	ds_read_b128 v[50:53], v242 offset:18432
	ds_read_b128 v[54:57], v242 offset:19456
	ds_read_b128 v[42:45], v242 offset:20480
	ds_read_b128 v[46:49], v242 offset:21504
	ds_read_b128 v[34:37], v242 offset:22528
	ds_read_b128 v[38:41], v242 offset:23552
	global_load_lds_dwordx4 v[218:219], off
	v_lshl_add_u64 v[220:221], s[62:63], 0, v[208:209]
	s_mov_b32 m0, s69
	s_addc_u32 s73, s63, 0
	global_load_lds_dwordx4 v[220:221], off
	v_lshl_add_u64 v[196:197], s[72:73], 0, v[204:205]
	s_mov_b32 m0, s78
	v_lshl_add_u64 v[222:223], s[66:67], 0, v[202:203]
	global_load_lds_dwordx4 v[196:197], off
	v_lshl_add_u64 v[196:197], s[72:73], 0, v[208:209]
	s_mov_b32 m0, s79
	v_lshl_add_u64 v[224:225], s[66:67], 0, v[206:207]
	global_load_lds_dwordx4 v[196:197], off
	s_mov_b32 m0, s25
	s_mov_b64 s[72:73], -1
	global_load_lds_dwordx4 v[222:223], off
	s_mov_b32 m0, s80
	s_and_b64 vcc, exec, s[64:65]
	global_load_lds_dwordx4 v[224:225], off
	s_cbranch_vccz .LBB0_1116
	s_waitcnt vmcnt(8)
	s_mov_b64 s[72:73], 0

; #define PG8_STAGE(bufoff, gbase, voff) do { _Pragma("unroll") for (int _i = 0; _i < 2; ++_i) \
;         __builtin_amdgcn_global_load_lds((const unsigned*)((const char*)(gbase) + (voff)[_i]), (PG8_LAS unsigned*)(lds + (bufoff) + ldsw + _i * 8192), 16, 0, 0); } while (0)
; #define PG8_LDA(dst, b, h) do { _Pragma("unroll") for (int m = 0; m < 4; ++m) _Pragma("unroll") for (int k = 0; k < 2; ++k) dst[m][k] = *(const PG8_LAS bf16x8*)(lds + PG8_SA(b, h) + aoff + m * 2048 + k * 1024); } while (0)
; #define PG8_LDB(dst, b, h) do { _Pragma("unroll") for (int n = 0; n < 2; ++n) _Pragma("unroll") for (int k = 0; k < 2; ++k) dst[n][k] = *(const PG8_LAS bf16x8*)(lds + PG8_SB(b, h) + boff + n * 2048 + k * 1024); } while (0)
; #define PG8_WAIT_VR(relax) do { if (relax) asm volatile("s_waitcnt vmcnt(%0)" :: "n"(8 + Epi::NST) : "memory"); else asm volatile("s_waitcnt vmcnt(8)" ::: "memory"); } while (0)
; #define PG8_WAIT_L(n) asm volatile("s_waitcnt lgkmcnt(" #n ")" ::: "memory")
; #define PG8_BAR __builtin_amdgcn_s_barrier()
; #define PG8_SCHED __builtin_amdgcn_sched_barrier(0)
; template <class Epi, class Sched, bool ALIGN_EPI = false, bool SP2 = false, bool F8 = false, bool GATHER = false>
; __device__ __forceinline__ void gemm_phase(PG8_LAS unsigned char* lds, const Gemm g, const Sched& S, const Epi& E, const int tid_in) {
;     ...
;             const char* a2 = last ? nA : cA + (size_t)(t + 2) * kstep; const char* b2 = last ? nB : cB + (size_t)(t + 2) * kstep;
;             const char* a3 = a2 + kstep; const char* b3 = b2 + kstep;
;             if (last && has_next) S.a_ready(nxt);
;             const bool relax = SP2 && ALIGN_EPI && t == 0 && ui > 0;
;             if constexpr (SP2) {
;             PG8_LDB(B0, 0, 0); PG8_LDB(B1, 0, 1); PG8_SCHED; PG8_LDA(At, 0, 0); if (!relax) PG8_STAGE(PG8_SA(1, 1), a1 + hstepA, vA1c);
;             PG8_WAIT_VR(relax); PG8_WAIT_L(0); PG8_BAR; PG8_MMA(0, 0, At, B0); PG8_MMA(0, 1, At, B1); PG8_BAR; PG8_SCHED;
;             PG8_LDA(At, 0, 1); PG8_STAGE(PG8_SB(0, 0), b2, voffB); PG8_STAGE(PG8_SB(0, 1), b2 + hstep, voffB); PG8_STAGE(PG8_SA(0, 0), a2, vA0s);
.Lpk_g2_1114:
	s_xor_b64 s[64:65], s[62:63], -1
	s_add_u32 s62, s42, s60
	s_addc_u32 s63, s43, s61
	s_add_u32 s62, s62, 0x100
	s_addc_u32 s63, s63, 0
	s_add_u32 s72, s92, s60
	s_addc_u32 s73, s93, s61
	s_cmpk_eq_i32 s60, 0x300
	s_cselect_b32 s67, s3, s63
	s_cselect_b32 s66, s49, s62
	s_cselect_b32 s63, s37, s73
	s_cselect_b32 s62, s91, s72
	s_waitcnt lgkmcnt(0)
	s_barrier
	s_setprio 1
	s_waitcnt lgkmcnt(0)
	v_mfma_f32_16x16x128_f8f6f4 v[192:195], v[26:33], v[58:65], 0
	v_mfma_f32_16x16x128_f8f6f4 v[188:191], v[18:25], v[58:65], 0
	v_mfma_f32_16x16x128_f8f6f4 v[184:187], v[26:33], v[50:57], 0
	v_mfma_f32_16x16x128_f8f6f4 v[180:183], v[18:25], v[50:57], 0
	v_mfma_f32_16x16x128_f8f6f4 v[160:163], v[26:33], v[42:49], 0
	v_mfma_f32_16x16x128_f8f6f4 v[156:159], v[18:25], v[42:49], 0
	v_mfma_f32_16x16x128_f8f6f4 v[152:155], v[26:33], v[34:41], 0
	v_mfma_f32_16x16x128_f8f6f4 v[148:151], v[18:25], v[34:41], 0
	s_setprio 0
	s_setprio 1
	v_mfma_f32_16x16x128_f8f6f4 v[176:179], v[8:15], v[58:65], 0
	v_mfma_f32_16x16x128_f8f6f4 v[172:175], v[0:7], v[58:65], 0
	v_mfma_f32_16x16x128_f8f6f4 v[168:171], v[8:15], v[50:57], 0
	v_mfma_f32_16x16x128_f8f6f4 v[164:167], v[0:7], v[50:57], 0
	v_mfma_f32_16x16x128_f8f6f4 v[144:147], v[8:15], v[42:49], 0
	v_mfma_f32_16x16x128_f8f6f4 v[140:143], v[0:7], v[42:49], 0
	v_mfma_f32_16x16x128_f8f6f4 v[136:139], v[8:15], v[34:41], 0
	v_mfma_f32_16x16x128_f8f6f4 v[132:135], v[0:7], v[34:41], 0
	s_setprio 0
	s_barrier
	s_mov_b32 m0, s57
	v_lshl_add_u64 v[218:219], s[62:63], 0, v[204:205]
	s_add_u32 s72, s62, 0x20000
	ds_read_b128 v[58:61], v242 offset:16384
	ds_read_b128 v[62:65], v242 offset:17408
	ds_read_b128 v[50:53], v242 offset:18432
	ds_read_b128 v[54:57], v242 offset:19456
	ds_read_b128 v[42:45], v242 offset:20480
	ds_read_b128 v[46:49], v242 offset:21504
	ds_read_b128 v[34:37], v242 offset:22528
	ds_read_b128 v[38:41], v242 offset:23552
	global_load_lds_dwordx4 v[218:219], off
	v_lshl_add_u64 v[220:221], s[62:63], 0, v[208:209]
	s_mov_b32 m0, s69
	s_addc_u32 s73, s63, 0
	global_load_lds_dwordx4 v[220:221], off
	v_lshl_add_u64 v[196:197], s[72:73], 0, v[204:205]
	s_mov_b32 m0, s78
	v_lshl_add_u64 v[222:223], s[66:67], 0, v[202:203]
	global_load_lds_dwordx4 v[196:197], off
	v_lshl_add_u64 v[196:197], s[72:73], 0, v[208:209]
	s_mov_b32 m0, s79
	v_lshl_add_u64 v[224:225], s[66:67], 0, v[206:207]
	global_load_lds_dwordx4 v[196:197], off
	s_mov_b32 m0, s25
	s_mov_b64 s[72:73], -1
	global_load_lds_dwordx4 v[222:223], off
	s_mov_b32 m0, s80
	s_and_b64 vcc, exec, s[64:65]
	global_load_lds_dwordx4 v[224:225], off
	s_cbranch_vccz .Lpk_g2_1116
	s_waitcnt vmcnt(8)
	s_mov_b64 s[72:73], 0
